# prep phase: touch loads ahead of gate rows and compression rows; V copy row loads issued together
# speedup vs baseline: 1.0030x; 1.0030x over previous
; #define LAS __attribute__((address_space(3)))
; #define LDS_WAIT() asm volatile("s_waitcnt lgkmcnt(0)" ::: "memory")
; DI void phase_prep(const Args& a, int layer, LAS unsigned char* lds) {
;     ...
;             const int srccol = (which == 0 ? C_VS : which == 1 ? C_VW : C_VB) + g * 64;
;             bf16_t* dst = (bf16_t*)(ws + (which == 0 ? WS_VST : which == 1 ? WS_VWT : WS_VBT)) + (size_t)bg * 64 * S + (size_t)st * 4096;
; #pragma unroll
;             for (int i = 0; i < 8; ++i) { const int tok = i * 8 + (lane >> 3), ch = lane & 7;
;                 const u32x4 v = *(const u32x4*)(P + (size_t)(b * S + st * 64 + tok) * NP + srccol + ch * 8);
;                 *(LAS u32x4*)(scr + tok * 72 + ch * 8) = v; }
;             LDS_WAIT();
; #pragma unroll
;             for (int f = 0; f < 8; ++f) {
;                 int d, kb0, kstep;
;                 if (which == 0) { const int j = f >> 2, dt = f & 3, hh = lane & 15, qd = lane >> 4; d = 16 * dt + hh; kb0 = 16 * j + 4 * qd; kstep = 32; }
;                 else { const int tl = f >> 2, j = (f >> 1) & 1, dt = f & 1, c = lane & 31, hi = lane >> 5; d = dt * 32 + c; kb0 = tl * 32 + 16 * j + 4 * hi; kstep = 8; }
;                 unsigned e[8];
; #pragma unroll
;                 for (int i = 0; i < 8; ++i) e[i] = scr[(kb0 + (i & 3) + kstep * (i >> 2)) * 72 + d];
;                 u32x4 o; o.x = e[0] | (e[1] << 16); o.y = e[2] | (e[3] << 16); o.z = e[4] | (e[5] << 16); o.w = e[6] | (e[7] << 16);
;                 *(u32x4*)(dst + (f * 64 + lane) * 8) = o;
.LBB0_347:
	v_ashrrev_i32_e32 v53, 31, v52
	v_add_u32_sdwa v0, v52, v53 dst_sel:DWORD dst_unused:UNUSED_PAD src0_sel:DWORD src1_sel:BYTE_3
	v_ashrrev_i32_e32 v0, 8, v0
	v_and_b32_e32 v9, 3, v0
	s_waitcnt lgkmcnt(0)
	v_bfe_u32 v1, v0, 1, 1
	s_movk_i32 s0, 0xc00
	v_lshlrev_b32_sdwa v3, v198, v52 dst_sel:DWORD dst_unused:UNUSED_PAD src0_sel:DWORD src1_sel:BYTE_0
	v_and_b32_e32 v12, 1, v0
	v_cmp_gt_i32_e64 s[0:1], s0, v52
	v_lshlrev_b32_e32 v2, 21, v9
	v_lshlrev_b32_sdwa v0, v199, v52 dst_sel:DWORD dst_unused:UNUSED_PAD src0_sel:DWORD src1_sel:BYTE_0
	v_lshl_or_b32 v58, v1, 14, v3
	s_and_saveexec_b64 s[22:23], s[0:1]
	s_xor_b64 s[42:43], exec, s[22:23]
	s_cbranch_execz .LBB0_349
	v_add_u32_e32 v1, 0x3ff, v52
	v_cmp_gt_u32_e64 s[38:39], s75, v1
	v_and_b32_e32 v1, 0xfffffc00, v52
	s_movk_i32 s0, 0x400
	v_cmp_eq_u32_e64 s[0:1], s0, v1
	v_mov_b32_e32 v1, 0xb80
	v_mov_b32_e32 v3, 0xa80
	v_cndmask_b32_e64 v1, v1, v3, s[0:1]
	v_cndmask_b32_e64 v1, v1, v214, s[38:39]
	v_lshlrev_b32_e32 v1, 1, v1
	v_lshl_or_b32 v10, v12, 7, v1
	v_or_b32_e32 v1, v58, v17
	v_mov_b32_e32 v11, v129
	v_mul_u32_u24_e32 v1, 0xd00, v1
	v_lshl_add_u64 v[54:55], v[4:5], 0, v[10:11]
	v_lshlrev_b32_e32 v10, 1, v1
	v_lshl_add_u64 v[10:11], v[54:55], 0, v[10:11]
	global_load_dwordx4 v[60:63], v[10:11], off
	v_or_b32_e32 v1, v58, v22
	v_mul_u32_u24_e32 v1, 0xd00, v1
	v_lshlrev_b32_e32 v10, 1, v1
	v_mov_b32_e32 v11, v129
	v_lshl_add_u64 v[10:11], v[54:55], 0, v[10:11]
	global_load_dwordx4 v[64:67], v[10:11], off
	v_or_b32_e32 v1, v58, v23
	v_mul_u32_u24_e32 v1, 0xd00, v1
	v_lshlrev_b32_e32 v10, 1, v1
	v_mov_b32_e32 v11, v129
	v_lshl_add_u64 v[10:11], v[54:55], 0, v[10:11]
	global_load_dwordx4 v[68:71], v[10:11], off
	v_or_b32_e32 v1, v58, v24
	v_mul_u32_u24_e32 v1, 0xd00, v1
	v_lshlrev_b32_e32 v10, 1, v1
	v_mov_b32_e32 v11, v129
	v_lshl_add_u64 v[10:11], v[54:55], 0, v[10:11]
	global_load_dwordx4 v[72:75], v[10:11], off
	v_or_b32_e32 v1, v58, v25
	v_mul_u32_u24_e32 v1, 0xd00, v1
	v_lshlrev_b32_e32 v10, 1, v1
	v_mov_b32_e32 v11, v129
	v_lshl_add_u64 v[10:11], v[54:55], 0, v[10:11]
	global_load_dwordx4 v[76:79], v[10:11], off
	v_or_b32_e32 v1, v58, v26
	v_mul_u32_u24_e32 v1, 0xd00, v1
	v_lshlrev_b32_e32 v10, 1, v1
	v_mov_b32_e32 v11, v129
	v_lshl_add_u64 v[10:11], v[54:55], 0, v[10:11]
	global_load_dwordx4 v[80:83], v[10:11], off
	v_or_b32_e32 v1, v58, v27
	v_mul_u32_u24_e32 v1, 0xd00, v1
	v_lshlrev_b32_e32 v10, 1, v1
	v_mov_b32_e32 v11, v129
	v_lshl_add_u64 v[10:11], v[54:55], 0, v[10:11]
	global_load_dwordx4 v[84:87], v[10:11], off
	v_or_b32_e32 v1, v58, v28
	v_mul_u32_u24_e32 v1, 0xd00, v1
	v_lshlrev_b32_e32 v10, 1, v1
	v_mov_b32_e32 v11, v129
	v_lshl_add_u64 v[10:11], v[54:55], 0, v[10:11]
	global_load_dwordx4 v[88:91], v[10:11], off
	v_cndmask_b32_e64 v3, v196, v204, s[0:1]
	v_cndmask_b32_e64 v128, v3, v205, s[38:39]
	v_mov_b32_e32 v3, v129
	v_cndmask_b32_e64 v9, v15, v19, s[38:39]
	s_movk_i32 s9, 0x90
	v_lshl_add_u32 v53, v9, 1, v16
	v_mov_b32_e32 v1, v129
	s_waitcnt vmcnt(0)
	ds_write_b128 v51, v[60:63]
	ds_write_b128 v51, v[64:67] offset:1152
	ds_write_b128 v51, v[68:71] offset:2304
	ds_write_b128 v51, v[72:75] offset:3456
	ds_write_b128 v51, v[76:79] offset:4608
	ds_write_b128 v51, v[80:83] offset:5760
	ds_write_b128 v51, v[84:87] offset:6912
	ds_write_b128 v51, v[88:91] offset:8064
	v_lshl_add_u64 v[10:11], s[98:99], 0, v[128:129]
	v_lshl_add_u64 v[2:3], v[10:11], 0, v[2:3]
	v_lshl_add_u64 v[0:1], v[2:3], 0, v[0:1]
	v_cndmask_b32_e64 v3, v18, v20, s[38:39]
	v_cndmask_b32_e64 v2, 8, 32, s[38:39]
	v_mad_u32_u24 v54, v3, s9, s9
	s_waitcnt lgkmcnt(0)
	v_mad_u32_u24 v9, v3, s9, v53
	v_add_u32_e32 v10, v53, v54
	v_add_u32_e32 v57, v3, v2
	ds_read_u16 v9, v9
	ds_read_u16 v10, v10
	v_mad_u32_u24 v55, v3, s9, v206
	v_mad_u32_u24 v56, v3, s9, v207
	v_add_u32_e32 v58, 1, v57
	v_add_u32_e32 v60, 2, v57
	v_add_u32_e32 v62, 3, v57
	v_add_u32_e32 v11, v53, v55
	v_add_u32_e32 v12, v53, v56
	v_mad_u32_u24 v13, v57, s9, v53
	v_mad_u32_u24 v59, v58, s9, v53
	v_mad_u32_u24 v61, v60, s9, v53
	v_mad_u32_u24 v63, v62, s9, v53
	ds_read_u16 v11, v11
	ds_read_u16 v12, v12
	ds_read_u16 v13, v13
	ds_read_u16 v59, v59
	ds_read_u16 v61, v61
	ds_read_u16 v63, v63
	s_waitcnt lgkmcnt(6)
	v_lshl_or_b32 v10, v10, 16, v9
	v_mov_b32_e32 v9, v129
	v_lshl_add_u64 v[0:1], v[0:1], 0, v[8:9]
	v_cndmask_b32_e64 v9, v29, v30, s[38:39]
	s_waitcnt lgkmcnt(4)
	v_lshl_or_b32 v11, v12, 16, v11
	s_waitcnt lgkmcnt(2)
	v_lshl_or_b32 v12, v59, 16, v13
	s_waitcnt lgkmcnt(0)
	v_lshl_or_b32 v13, v63, 16, v61
	v_lshl_add_u32 v9, v9, 1, v16
	global_store_dwordx4 v[0:1], v[10:13], off
	v_mad_u32_u24 v3, v3, s9, v9
	ds_read_u16 v3, v3
	v_add_u32_e32 v10, v9, v54
	v_add_u32_e32 v11, v9, v55
	v_add_u32_e32 v12, v9, v56
	v_mad_u32_u24 v13, v57, s9, v9
	v_mad_u32_u24 v54, v58, s9, v9
	v_mad_u32_u24 v55, v60, s9, v9
	v_mad_u32_u24 v56, v62, s9, v9
	ds_read_u16 v10, v10
	ds_read_u16 v11, v11
	ds_read_u16 v12, v12
	ds_read_u16 v13, v13
	ds_read_u16 v54, v54
	ds_read_u16 v55, v55
	ds_read_u16 v56, v56
	s_waitcnt lgkmcnt(6)
	v_lshl_or_b32 v10, v10, 16, v3
	s_waitcnt lgkmcnt(4)
	v_lshl_or_b32 v11, v12, 16, v11
	s_waitcnt lgkmcnt(2)
	v_lshl_or_b32 v12, v54, 16, v13
	v_cndmask_b32_e64 v3, v31, v20, s[38:39]
	s_waitcnt lgkmcnt(0)
; #define LDS_WAIT() asm volatile("s_waitcnt lgkmcnt(0)" ::: "memory")
; DI void phase_prep(const Args& a, int layer, LAS unsigned char* lds) {
;     ...
; #pragma unroll
;             for (int f = 0; f < 8; ++f) {
;                 int d, kb0, kstep;
;                 if (which == 0) { const int j = f >> 2, dt = f & 3, hh = lane & 15, qd = lane >> 4; d = 16 * dt + hh; kb0 = 16 * j + 4 * qd; kstep = 32; }
;                 else { const int tl = f >> 2, j = (f >> 1) & 1, dt = f & 1, c = lane & 31, hi = lane >> 5; d = dt * 32 + c; kb0 = tl * 32 + 16 * j + 4 * hi; kstep = 8; }
;                 unsigned e[8];
; #pragma unroll
;                 for (int i = 0; i < 8; ++i) e[i] = scr[(kb0 + (i & 3) + kstep * (i >> 2)) * 72 + d];
;                 u32x4 o; o.x = e[0] | (e[1] << 16); o.y = e[2] | (e[3] << 16); o.z = e[4] | (e[5] << 16); o.w = e[6] | (e[7] << 16);
;                 *(u32x4*)(dst + (f * 64 + lane) * 8) = o;
;             }
;             LDS_WAIT();
	v_lshl_or_b32 v13, v56, 16, v55
	global_store_dwordx4 v[0:1], v[10:13], off offset:1024
	v_add_u32_e32 v58, v3, v2
	v_mad_u32_u24 v54, v3, s9, s9
	v_cndmask_b32_e64 v10, v15, v32, s[38:39]
	v_lshl_add_u32 v56, v10, 1, v16
	v_mad_u32_u24 v55, v3, s9, v206
	v_mad_u32_u24 v57, v3, s9, v207
	v_add_u32_e32 v60, 1, v58
	v_add_u32_e32 v62, 2, v58
	v_add_u32_e32 v64, 3, v58
	v_mad_u32_u24 v10, v3, s9, v56
	v_add_u32_e32 v11, v56, v54
	v_add_u32_e32 v12, v56, v55
	v_add_u32_e32 v13, v56, v57
	v_mad_u32_u24 v59, v58, s9, v56
	v_mad_u32_u24 v61, v60, s9, v56
	v_mad_u32_u24 v63, v62, s9, v56
	v_mad_u32_u24 v65, v64, s9, v56
	ds_read_u16 v10, v10
	ds_read_u16 v11, v11
	ds_read_u16 v12, v12
	ds_read_u16 v13, v13
	ds_read_u16 v59, v59
	ds_read_u16 v61, v61
	ds_read_u16 v63, v63
	ds_read_u16 v65, v65
	s_waitcnt lgkmcnt(6)
	v_lshl_or_b32 v10, v11, 16, v10
	s_waitcnt lgkmcnt(4)
	v_lshl_or_b32 v11, v13, 16, v12
	s_waitcnt lgkmcnt(2)
	v_lshl_or_b32 v12, v61, 16, v59
	s_waitcnt lgkmcnt(0)
	v_lshl_or_b32 v13, v65, 16, v63
	global_store_dwordx4 v[0:1], v[10:13], off offset:2048
	s_nop 1
	v_cndmask_b32_e64 v10, v29, v33, s[38:39]
	v_lshl_add_u32 v59, v10, 1, v16
	v_mad_u32_u24 v3, v3, s9, v59
	v_add_u32_e32 v10, v59, v54
	ds_read_u16 v3, v3
	ds_read_u16 v10, v10
	v_add_u32_e32 v11, v59, v55
	v_add_u32_e32 v12, v59, v57
	v_mad_u32_u24 v13, v58, s9, v59
	v_mad_u32_u24 v54, v60, s9, v59
	v_mad_u32_u24 v55, v62, s9, v59
	v_mad_u32_u24 v57, v64, s9, v59
	ds_read_u16 v11, v11
	ds_read_u16 v12, v12
	ds_read_u16 v13, v13
	ds_read_u16 v54, v54
	ds_read_u16 v55, v55
	ds_read_u16 v57, v57
	s_waitcnt lgkmcnt(6)
	v_lshl_or_b32 v10, v10, 16, v3
	v_cndmask_b32_e64 v3, v34, v35, s[38:39]
	v_add_u32_e32 v61, v3, v2
	s_waitcnt lgkmcnt(4)
	v_lshl_or_b32 v11, v12, 16, v11
	s_waitcnt lgkmcnt(2)
	v_lshl_or_b32 v12, v54, 16, v13
	s_waitcnt lgkmcnt(0)
	v_lshl_or_b32 v13, v57, 16, v55
	v_mad_u32_u24 v57, v3, s9, s9
	v_mad_u32_u24 v58, v3, s9, v206
	v_mad_u32_u24 v60, v3, s9, v207
	v_add_u32_e32 v62, 1, v61
	global_store_dwordx4 v[0:1], v[10:13], off offset:3072
	v_mad_u32_u24 v54, v61, s9, v53
	v_mad_u32_u24 v55, v62, s9, v53
	v_mad_u32_u24 v10, v3, s9, v53
	v_add_u32_e32 v11, v53, v57
	v_add_u32_e32 v12, v53, v58
	v_add_u32_e32 v13, v53, v60
	v_add_u32_e32 v63, 2, v61
	v_add_u32_e32 v65, 3, v61
	ds_read_u16 v10, v10
	ds_read_u16 v11, v11
	ds_read_u16 v12, v12
	ds_read_u16 v13, v13
	ds_read_u16 v54, v54
	ds_read_u16 v55, v55
	v_mad_u32_u24 v64, v63, s9, v53
	v_mad_u32_u24 v53, v65, s9, v53
	ds_read_u16 v64, v64
	ds_read_u16 v53, v53
	s_waitcnt lgkmcnt(6)
	v_lshl_or_b32 v10, v11, 16, v10
	s_waitcnt lgkmcnt(4)
	v_lshl_or_b32 v11, v13, 16, v12
	s_waitcnt lgkmcnt(2)
	v_lshl_or_b32 v12, v55, 16, v54
	v_add_co_u32_e64 v54, s[0:1], s26, v0
	s_waitcnt lgkmcnt(0)
	v_lshl_or_b32 v13, v53, 16, v64
	v_addc_co_u32_e64 v55, s[0:1], 0, v1, s[0:1]
	global_store_dwordx4 v[54:55], v[10:13], off
	v_mad_u32_u24 v0, v3, s9, v9
	v_add_u32_e32 v1, v9, v57
	v_add_u32_e32 v10, v9, v60
	ds_read_u16 v11, v10
	v_mad_u32_u24 v10, v61, s9, v9
	ds_read_u16 v12, v10
	v_mad_u32_u24 v10, v62, s9, v9
	v_add_u32_e32 v3, v9, v58
	ds_read_u16 v13, v10
	v_mad_u32_u24 v10, v63, s9, v9
	v_mad_u32_u24 v9, v65, s9, v9
	ds_read_u16 v3, v3
	ds_read_u16 v53, v10
	ds_read_u16 v9, v9
	ds_read_u16 v0, v0
	ds_read_u16 v1, v1
	s_waitcnt lgkmcnt(5)
	v_lshl_or_b32 v12, v13, 16, v12
	s_waitcnt lgkmcnt(2)
	v_lshl_or_b32 v13, v9, 16, v53
	v_cndmask_b32_e64 v9, v36, v35, s[38:39]
	v_add_u32_e32 v53, v9, v2
	v_mad_u32_u24 v2, v53, s9, v56
	ds_read_u16 v2, v2
	s_waitcnt lgkmcnt(1)
	v_lshl_or_b32 v10, v1, 16, v0
	v_lshl_or_b32 v11, v11, 16, v3
	global_store_dwordx4 v[54:55], v[10:13], off offset:1024
	v_add_u32_e32 v57, 1, v53
	v_add_u32_e32 v60, 2, v53
	v_mad_u32_u24 v10, v9, s9, s9
	v_mad_u32_u24 v11, v9, s9, v206
	v_mad_u32_u24 v12, v9, s9, v207
	v_add_u32_e32 v62, 3, v53
	v_mad_u32_u24 v0, v9, s9, v56
	v_add_u32_e32 v1, v56, v10
	v_add_u32_e32 v3, v56, v11
	v_add_u32_e32 v13, v56, v12
	v_mad_u32_u24 v58, v57, s9, v56
	v_mad_u32_u24 v61, v60, s9, v56
	v_mad_u32_u24 v56, v62, s9, v56
	ds_read_u16 v0, v0
	ds_read_u16 v1, v1
	ds_read_u16 v3, v3
	ds_read_u16 v13, v13
	ds_read_u16 v58, v58
	ds_read_u16 v61, v61
	ds_read_u16 v56, v56
	s_waitcnt lgkmcnt(5)
	v_lshl_or_b32 v0, v1, 16, v0
	s_waitcnt lgkmcnt(3)
	v_lshl_or_b32 v1, v13, 16, v3
	s_waitcnt lgkmcnt(2)
	v_lshl_or_b32 v2, v58, 16, v2
	s_waitcnt lgkmcnt(0)
	v_lshl_or_b32 v3, v56, 16, v61
	global_store_dwordx4 v[54:55], v[0:3], off offset:2048
	s_nop 1
	v_mad_u32_u24 v0, v9, s9, v59
	v_add_u32_e32 v1, v59, v10
	v_add_u32_e32 v2, v59, v11
	v_add_u32_e32 v3, v59, v12
	v_mad_u32_u24 v9, v53, s9, v59
	v_mad_u32_u24 v10, v57, s9, v59
	v_mad_u32_u24 v11, v60, s9, v59
	v_mad_u32_u24 v12, v62, s9, v59
	ds_read_u16 v0, v0
	ds_read_u16 v1, v1
	ds_read_u16 v2, v2
	ds_read_u16 v3, v3
	ds_read_u16 v9, v9
	ds_read_u16 v10, v10
	ds_read_u16 v11, v11
	ds_read_u16 v12, v12
	s_waitcnt lgkmcnt(6)
	v_lshl_or_b32 v0, v1, 16, v0
	s_waitcnt lgkmcnt(4)
	v_lshl_or_b32 v1, v3, 16, v2
	s_waitcnt lgkmcnt(2)
	v_lshl_or_b32 v2, v10, 16, v9
	s_waitcnt lgkmcnt(0)
	v_lshl_or_b32 v3, v12, 16, v11
	global_store_dwordx4 v[54:55], v[0:3], off offset:3072
	s_waitcnt lgkmcnt(0)
